# P1 epilogue (EpiAda): the four column-only bias quads loaded once before the first row block instead of a serialized load->wait per stored quad
# speedup vs baseline: 1.0069x; 1.0015x over previous
;     __device__ __forceinline__ void operator()(const AccT& acc, const pg8::Unit& u, int wr, int wc, int fr, int fq) const {
; #pragma unroll
;         for (int ai = 0; ai < 2; ++ai)
; #pragma unroll
;             for (int m = 0; m < 4; ++m) { const int row = u.pm * 256 + ai * 128 + wr * 64 + m * 16 + fr; if (row >= NCOND) continue;
; #pragma unroll
;                 for (int bj = 0; bj < 2; ++bj)
; #pragma unroll
;                     for (int n = 0; n < 2; ++n) { const int col = u.pn * 256 + bj * 128 + wc * 32 + 8 * fq + 4 * n;
;                         *(f32x4*)(ada + (size_t)row * NADA + col) = acc[ai][bj][m][n] + *(const f32x4*)(bias + col); } }
;     }
.LBB0_200:
	v_lshl_add_u32 v148, s28, 8, v142
	v_lshl_add_u32 v140, s26, 8, v144
	v_cmp_gt_i32_e32 vcc, s52, v148
	v_ashrrev_i32_e32 v141, 31, v140
	s_and_saveexec_b64 s[26:27], vcc
	s_cbranch_execz .LBB0_202
	v_lshlrev_b64 v[154:155], 2, v[140:141]
	v_lshl_add_u64 v[156:157], s[4:5], 0, v[154:155]
	global_load_dwordx4 v[184:187], v[156:157], off
	global_load_dwordx4 v[188:191], v[156:157], off offset:16
	global_load_dwordx4 v[192:195], v[156:157], off offset:512
	global_load_dwordx4 v[196:199], v[156:157], off offset:528
	v_mov_b64_e32 v[158:159], s[8:9]
	v_mad_i64_i32 v[158:159], s[30:31], v148, s53, v[158:159]
	v_lshl_add_u64 v[154:155], v[158:159], 0, v[154:155]
	s_waitcnt vmcnt(0)
	v_pk_add_f32 v[126:127], v[126:127], v[186:187]
	v_pk_add_f32 v[124:125], v[124:125], v[184:185]
	global_store_dwordx4 v[154:155], v[124:127], off
	v_pk_add_f32 v[122:123], v[122:123], v[190:191]
	v_pk_add_f32 v[120:121], v[120:121], v[188:189]
	global_store_dwordx4 v[154:155], v[120:123], off offset:16
	v_pk_add_f32 v[118:119], v[118:119], v[194:195]
	v_pk_add_f32 v[116:117], v[116:117], v[192:193]
	global_store_dwordx4 v[154:155], v[116:119], off offset:512
	v_pk_add_f32 v[114:115], v[114:115], v[198:199]
	v_pk_add_f32 v[112:113], v[112:113], v[196:197]
	global_store_dwordx4 v[154:155], v[112:115], off offset:528
.LBB0_202:
	s_or_b64 exec, exec, s[26:27]
	s_nop 0
	v_or_b32_e32 v112, 16, v148
	v_cmp_gt_i32_e32 vcc, s52, v112
	s_and_saveexec_b64 s[26:27], vcc
	s_cbranch_execz .LBB0_204
	v_lshlrev_b64 v[118:119], 2, v[140:141]
	v_lshl_add_u64 v[120:121], s[4:5], 0, v[118:119]
	v_mov_b64_e32 v[122:123], s[8:9]
	v_mad_i64_i32 v[112:113], s[30:31], v112, s53, v[122:123]
	v_lshl_add_u64 v[112:113], v[112:113], 0, v[118:119]
	v_pk_add_f32 v[110:111], v[110:111], v[186:187]
	v_pk_add_f32 v[108:109], v[108:109], v[184:185]
	global_store_dwordx4 v[112:113], v[108:111], off
	v_pk_add_f32 v[106:107], v[106:107], v[190:191]
	v_pk_add_f32 v[104:105], v[104:105], v[188:189]
	global_store_dwordx4 v[112:113], v[104:107], off offset:16
	v_pk_add_f32 v[102:103], v[102:103], v[194:195]
	v_pk_add_f32 v[100:101], v[100:101], v[192:193]
	global_store_dwordx4 v[112:113], v[100:103], off offset:512
	v_pk_add_f32 v[98:99], v[98:99], v[198:199]
	v_pk_add_f32 v[96:97], v[96:97], v[196:197]
	global_store_dwordx4 v[112:113], v[96:99], off offset:528
.LBB0_204:
	s_or_b64 exec, exec, s[26:27]
	s_nop 0
	v_or_b32_e32 v96, 32, v148
	v_cmp_gt_i32_e32 vcc, s52, v96
	s_and_saveexec_b64 s[26:27], vcc
	s_cbranch_execz .LBB0_206
	v_lshlrev_b64 v[102:103], 2, v[140:141]
	v_lshl_add_u64 v[104:105], s[4:5], 0, v[102:103]
	v_mov_b64_e32 v[106:107], s[8:9]
	v_mad_i64_i32 v[96:97], s[30:31], v96, s53, v[106:107]
	v_lshl_add_u64 v[96:97], v[96:97], 0, v[102:103]
	v_pk_add_f32 v[94:95], v[94:95], v[186:187]
	v_pk_add_f32 v[92:93], v[92:93], v[184:185]
	global_store_dwordx4 v[96:97], v[92:95], off
	v_pk_add_f32 v[90:91], v[90:91], v[190:191]
	v_pk_add_f32 v[88:89], v[88:89], v[188:189]
	global_store_dwordx4 v[96:97], v[88:91], off offset:16
	v_pk_add_f32 v[86:87], v[86:87], v[194:195]
	v_pk_add_f32 v[84:85], v[84:85], v[192:193]
	global_store_dwordx4 v[96:97], v[84:87], off offset:512
	v_pk_add_f32 v[82:83], v[82:83], v[198:199]
	v_pk_add_f32 v[80:81], v[80:81], v[196:197]
	global_store_dwordx4 v[96:97], v[80:83], off offset:528
.LBB0_206:
	s_or_b64 exec, exec, s[26:27]
	s_nop 0
	v_or_b32_e32 v80, 48, v148
	v_cmp_gt_i32_e32 vcc, s52, v80
	s_and_saveexec_b64 s[26:27], vcc
	s_cbranch_execz .LBB0_208
	v_lshlrev_b64 v[86:87], 2, v[140:141]
	v_lshl_add_u64 v[88:89], s[4:5], 0, v[86:87]
	v_mov_b64_e32 v[90:91], s[8:9]
	v_mad_i64_i32 v[80:81], s[30:31], v80, s53, v[90:91]
	v_lshl_add_u64 v[80:81], v[80:81], 0, v[86:87]
	v_pk_add_f32 v[78:79], v[78:79], v[186:187]
	v_pk_add_f32 v[76:77], v[76:77], v[184:185]
	global_store_dwordx4 v[80:81], v[76:79], off
	v_pk_add_f32 v[74:75], v[74:75], v[190:191]
	v_pk_add_f32 v[72:73], v[72:73], v[188:189]
	global_store_dwordx4 v[80:81], v[72:75], off offset:16
	v_pk_add_f32 v[70:71], v[70:71], v[194:195]
	v_pk_add_f32 v[68:69], v[68:69], v[192:193]
	global_store_dwordx4 v[80:81], v[68:71], off offset:512
	v_pk_add_f32 v[66:67], v[66:67], v[198:199]
	v_pk_add_f32 v[64:65], v[64:65], v[196:197]
	global_store_dwordx4 v[80:81], v[64:67], off offset:528
;     __device__ __forceinline__ void operator()(const AccT& acc, const pg8::Unit& u, int wr, int wc, int fr, int fq) const {
;     ...
;             for (int m = 0; m < 4; ++m) { const int row = u.pm * 256 + ai * 128 + wr * 64 + m * 16 + fr; if (row >= NCOND) continue;
; #pragma unroll
;                 for (int bj = 0; bj < 2; ++bj)
; #pragma unroll
;                     for (int n = 0; n < 2; ++n) { const int col = u.pn * 256 + bj * 128 + wc * 32 + 8 * fq + 4 * n;
;                         *(f32x4*)(ada + (size_t)row * NADA + col) = acc[ai][bj][m][n] + *(const f32x4*)(bias + col); } }
.LBB0_208:
	s_or_b64 exec, exec, s[26:27]
	s_nop 0
	v_add_u32_e32 v64, 0x80, v148
	v_cmp_gt_i32_e32 vcc, s52, v64
	s_and_saveexec_b64 s[26:27], vcc
	s_cbranch_execz .LBB0_210
	v_lshlrev_b64 v[70:71], 2, v[140:141]
	v_lshl_add_u64 v[72:73], s[4:5], 0, v[70:71]
	v_mov_b64_e32 v[74:75], s[8:9]
	v_mad_i64_i32 v[64:65], s[30:31], v64, s53, v[74:75]
	v_lshl_add_u64 v[64:65], v[64:65], 0, v[70:71]
	v_pk_add_f32 v[62:63], v[62:63], v[186:187]
	v_pk_add_f32 v[60:61], v[60:61], v[184:185]
	global_store_dwordx4 v[64:65], v[60:63], off
	v_pk_add_f32 v[58:59], v[58:59], v[190:191]
	v_pk_add_f32 v[56:57], v[56:57], v[188:189]
	global_store_dwordx4 v[64:65], v[56:59], off offset:16
	v_pk_add_f32 v[54:55], v[54:55], v[194:195]
	v_pk_add_f32 v[52:53], v[52:53], v[192:193]
	global_store_dwordx4 v[64:65], v[52:55], off offset:512
	v_pk_add_f32 v[50:51], v[50:51], v[198:199]
	v_pk_add_f32 v[48:49], v[48:49], v[196:197]
	global_store_dwordx4 v[64:65], v[48:51], off offset:528
.LBB0_210:
	s_or_b64 exec, exec, s[26:27]
	s_nop 0
	v_add_u32_e32 v48, 0x90, v148
	v_cmp_gt_i32_e32 vcc, s52, v48
	s_and_saveexec_b64 s[26:27], vcc
	s_cbranch_execz .LBB0_212
	v_lshlrev_b64 v[54:55], 2, v[140:141]
	v_lshl_add_u64 v[56:57], s[4:5], 0, v[54:55]
	v_mov_b64_e32 v[58:59], s[8:9]
	v_mad_i64_i32 v[48:49], s[30:31], v48, s53, v[58:59]
	v_lshl_add_u64 v[48:49], v[48:49], 0, v[54:55]
	v_pk_add_f32 v[46:47], v[46:47], v[186:187]
	v_pk_add_f32 v[44:45], v[44:45], v[184:185]
	global_store_dwordx4 v[48:49], v[44:47], off
	v_pk_add_f32 v[42:43], v[42:43], v[190:191]
	v_pk_add_f32 v[40:41], v[40:41], v[188:189]
	global_store_dwordx4 v[48:49], v[40:43], off offset:16
	v_pk_add_f32 v[38:39], v[38:39], v[194:195]
	v_pk_add_f32 v[36:37], v[36:37], v[192:193]
	global_store_dwordx4 v[48:49], v[36:39], off offset:512
	v_pk_add_f32 v[34:35], v[34:35], v[198:199]
	v_pk_add_f32 v[32:33], v[32:33], v[196:197]
	global_store_dwordx4 v[48:49], v[32:35], off offset:528
.LBB0_212:
	s_or_b64 exec, exec, s[26:27]
	s_nop 0
	v_add_u32_e32 v32, 0xa0, v148
	v_cmp_gt_i32_e32 vcc, s52, v32
	s_and_saveexec_b64 s[26:27], vcc
	s_cbranch_execz .LBB0_214
	v_lshlrev_b64 v[38:39], 2, v[140:141]
	v_lshl_add_u64 v[40:41], s[4:5], 0, v[38:39]
	v_mov_b64_e32 v[42:43], s[8:9]
	v_mad_i64_i32 v[32:33], s[30:31], v32, s53, v[42:43]
	v_lshl_add_u64 v[32:33], v[32:33], 0, v[38:39]
	v_pk_add_f32 v[30:31], v[30:31], v[186:187]
	v_pk_add_f32 v[28:29], v[28:29], v[184:185]
	global_store_dwordx4 v[32:33], v[28:31], off
	v_pk_add_f32 v[26:27], v[26:27], v[190:191]
	v_pk_add_f32 v[24:25], v[24:25], v[188:189]
	global_store_dwordx4 v[32:33], v[24:27], off offset:16
	v_pk_add_f32 v[22:23], v[22:23], v[194:195]
	v_pk_add_f32 v[20:21], v[20:21], v[192:193]
	global_store_dwordx4 v[32:33], v[20:23], off offset:512
	v_pk_add_f32 v[18:19], v[18:19], v[198:199]
	v_pk_add_f32 v[16:17], v[16:17], v[196:197]
	global_store_dwordx4 v[32:33], v[16:19], off offset:528
.LBB0_214:
	s_or_b64 exec, exec, s[26:27]
	s_nop 0
	v_add_u32_e32 v16, 0xb0, v148
	v_cmp_gt_i32_e32 vcc, s52, v16
	s_and_saveexec_b64 s[26:27], vcc
	s_cbranch_execz .LBB0_216
	v_lshlrev_b64 v[22:23], 2, v[140:141]
	v_lshl_add_u64 v[24:25], s[4:5], 0, v[22:23]
	v_mov_b64_e32 v[26:27], s[8:9]
	v_mad_i64_i32 v[16:17], s[30:31], v16, s53, v[26:27]
	v_lshl_add_u64 v[16:17], v[16:17], 0, v[22:23]
	v_pk_add_f32 v[14:15], v[14:15], v[186:187]
	v_pk_add_f32 v[12:13], v[12:13], v[184:185]
	global_store_dwordx4 v[16:17], v[12:15], off
	v_pk_add_f32 v[10:11], v[10:11], v[190:191]
	v_pk_add_f32 v[8:9], v[8:9], v[188:189]
	global_store_dwordx4 v[16:17], v[8:11], off offset:16
	v_pk_add_f32 v[6:7], v[6:7], v[194:195]
	v_pk_add_f32 v[4:5], v[4:5], v[192:193]
	global_store_dwordx4 v[16:17], v[4:7], off offset:512
	v_pk_add_f32 v[2:3], v[2:3], v[198:199]
	v_pk_add_f32 v[0:1], v[0:1], v[196:197]
	global_store_dwordx4 v[16:17], v[0:3], off offset:528
